# NA: V^T tiles staged through LDS-DMA (whole 128-byte lines fetched once per key row, ds_read_b128 fragments) instead of per-lane strided 16-byte global loads
# speedup vs baseline: 1.0587x; 1.0032x over previous
; #define LAS __attribute__((address_space(3)))
; __device__ __forceinline__ f32x16 zero16() { return (f32x16){0.f, 0.f, 0.f, 0.f, 0.f, 0.f, 0.f, 0.f, 0.f, 0.f, 0.f, 0.f, 0.f, 0.f, 0.f, 0.f}; }
; __device__ __forceinline__ void na_item(const bf16_t* __restrict__ proj, const bf16_t* __restrict__ projT, bf16_t* aout, const float* __restrict__ relb  , int item, int seqlen, LAS unsigned char* lds, int w, int lane) {
;     const int c = lane & 31, hh = lane >> 5;
;     const int R = item >> 3, h = item & 7;
;     const int rps = seqlen >> 6, seq = R / rps, r = R % rps;
;     int rs = r - 4; rs = rs < 0 ? 0 : rs; rs = rs > rps - 8 ? rps - 8 : rs;
;     const int qtok0 = seq * seqlen + r * 64, ktok0 = seq * seqlen + rs * 64;
;     LAS float* bias = (LAS float*)(lds + w * NA_LDS_WAVE) + 64;
;     LAS bf16_t* Otile = (LAS bf16_t*)(lds + w * NA_LDS_WAVE + 3072);
;     for (int i = lane; i < 768; i += 64) { const int j = i - 64; bias[j] = (j >= 0 && j < 465) ? relb[h * 465 + j] * 1.4426950408889634f : 0.f; }
;     bf16x8 qf[2][4];
; #pragma unroll
;     for (int qh = 0; qh < 2; ++qh) { const bf16_t* qp = proj + (size_t)(qtok0 + 32 * qh + c) * NPROJ + h * 64 + 8 * hh;
; #pragma unroll
;         for (int s = 0; s < 4; ++s) qf[qh][s] = *(const bf16x8*)(qp + 16 * s); }
;     f32x16 O[2][2];
;     float mrun[2], lrun[2]; int cs[2];
; #pragma unroll
;     for (int qh = 0; qh < 2; ++qh) { O[qh][0] = zero16(); O[qh][1] = zero16(); mrun[qh] = -1e30f; lrun[qh] = 0.f;
;         int x = 32 * qh + c - 8; x = x < 0 ? 0 : x; x = x > 48 ? 48 : x; cs[qh] = x; }
.LBB0_345:
	s_or_b64 exec, exec, s[0:1]
	v_mov_b32_e32 v0, v232
	s_waitcnt lgkmcnt(0)
	s_barrier
	v_readlane_b32 s4, v254, 39
	v_readfirstlane_b32 s0, v0
	s_ashr_i32 s1, s0, 6
	s_lshl_b64 s[94:95], s[92:93], 24
	s_add_i32 s25, s1, s4
	v_mov_b32_e32 v234, 0x358637bd
	s_cmpk_gt_i32 s25, 0x7ff
	s_cbranch_scc1 .LBB0_360
	v_bfe_u32 v4, v0, 5, 1
	s_bfe_u32 s0, s0, 0x30006
	v_and_b32_e32 v3, 63, v0
	v_and_b32_e32 v190, 31, v0
	s_mulk_i32 s1, 0x4000
	v_lshlrev_b32_e32 v2, 3, v4
	v_lshlrev_b32_e32 v196, 3, v4
	v_lshlrev_b32_e32 v4, 3, v0
	s_lshl_b32 s43, s0, 6
	s_add_i32 s27, s1, 0
	v_or_b32_e32 v193, 32, v3
	v_and_b32_e32 v4, 56, v4
	v_bfe_u32 v199, v0, 3, 3
	v_or_b32_e32 v0, s43, v190
	v_max_u32_e32 v191, 8, v190
	v_min_u32_e32 v194, 56, v193
	v_add_u32_e32 v5, s27, v2
	v_mul_u32_u24_e32 v6, 0x90, v190
	v_mul_u32_u24_e32 v7, 0x90, v193
	v_lshl_add_u32 v8, v4, 1, s27
	v_mul_u32_u24_e32 v9, 0x90, v199
	v_lshlrev_b32_e32 v0, 14, v0
	v_sub_u32_e64 v192, v190, 8 clamp
	v_add_u32_e32 v195, -8, v194
	v_add_u32_e32 v197, 8, v191
	v_add_u32_e32 v198, 8, v194
	s_mul_i32 s42, s0, 0x1d1
	v_or_b32_e32 v200, 0xffffffc0, v3
	v_lshl_add_u32 v201, v3, 2, s27
	v_lshrrev_b32_e32 v236, 1, v190
	v_and_b32_e32 v236, 4, v236
	v_lshlrev_b32_e32 v237, 1, v190
	v_and_b32_e32 v237, 8, v237
	v_and_b32_e32 v238, 19, v190
	v_or3_b32 v236, v236, v237, v238
	v_or_b32_e32 v202, 32, v236
	v_lshlrev_b32_e32 v191, 7, v190
	v_lshl_add_u32 v191, v196, 1, v191
	v_add_u32_e32 v191, s27, v191
	v_add_u32_e32 v191, 0xc00, v191
	v_lshlrev_b32_e32 v162, 1, v2
	v_lshlrev_b32_e32 v164, 1, v0
	v_add_u32_e32 v203, v5, v6
	v_add_u32_e32 v204, v5, v7
	v_lshlrev_b32_e32 v166, 1, v4
	v_add_u32_e32 v205, v8, v9

; #define LAS __attribute__((address_space(3)))
; __device__ __forceinline__ f32x16 zero16() { return (f32x16){0.f, 0.f, 0.f, 0.f, 0.f, 0.f, 0.f, 0.f, 0.f, 0.f, 0.f, 0.f, 0.f, 0.f, 0.f, 0.f}; }
; __device__ __forceinline__ void na_load(NaFrags& f, const bf16_t* __restrict__ proj, const bf16_t* __restrict__ projT, int ktok, int h, int c, int hh) {
;     const bf16_t* kp = proj + (size_t)(ktok + c) * NPROJ + 512 + h * 64 + 8 * hh;
; #pragma unroll
;     for (int s = 0; s < 4; ++s) f.k[s] = *(const bf16x8*)(kp + 16 * s);
; #pragma unroll
;     for (int dt = 0; dt < 2; ++dt)
; #pragma unroll
;         for (int s2 = 0; s2 < 2; ++s2) { const bf16_t* vp = projT + (size_t)(h * 64 + dt * 32 + c) * MG + (ktok + 16 * s2 + 4 * hh);
;             f.v[dt][s2][0] = *(const u32x2*)vp; f.v[dt][s2][1] = *(const u32x2*)(vp + 8); }
; }
; __device__ __forceinline__ void na_item(const bf16_t* __restrict__ proj, const bf16_t* __restrict__ projT, bf16_t* aout, const float* __restrict__ relb  , int item, int seqlen, LAS unsigned char* lds, int w, int lane) {
;     const int c = lane & 31, hh = lane >> 5;
;     const int R = item >> 3, h = item & 7;
;     const int rps = seqlen >> 6, seq = R / rps, r = R % rps;
;     int rs = r - 4; rs = rs < 0 ? 0 : rs; rs = rs > rps - 8 ? rps - 8 : rs;
;     const int qtok0 = seq * seqlen + r * 64, ktok0 = seq * seqlen + rs * 64;
;     LAS float* bias = (LAS float*)(lds + w * NA_LDS_WAVE) + 64;
;     LAS bf16_t* Otile = (LAS bf16_t*)(lds + w * NA_LDS_WAVE + 3072);
;     for (int i = lane; i < 768; i += 64) { const int j = i - 64; bias[j] = (j >= 0 && j < 465) ? relb[h * 465 + j] * 1.4426950408889634f : 0.f; }
;     bf16x8 qf[2][4];
; #pragma unroll
;     for (int qh = 0; qh < 2; ++qh) { const bf16_t* qp = proj + (size_t)(qtok0 + 32 * qh + c) * NPROJ + h * 64 + 8 * hh;
; #pragma unroll
;         for (int s = 0; s < 4; ++s) qf[qh][s] = *(const bf16x8*)(qp + 16 * s); }
;     f32x16 O[2][2];
;     float mrun[2], lrun[2]; int cs[2];
; #pragma unroll
;     for (int qh = 0; qh < 2; ++qh) { O[qh][0] = zero16(); O[qh][1] = zero16(); mrun[qh] = -1e30f; lrun[qh] = 0.f;
;         int x = 32 * qh + c - 8; x = x < 0 ? 0 : x; x = x > 48 ? 48 : x; cs[qh] = x; }
;     NaFrags cur, nxt;
;     na_load(cur, proj, projT, ktok0, h, c, hh);
.LBB0_351:
	s_or_b64 exec, exec, s[28:29]
	s_add_u32 s10, s30, s0
	s_addc_u32 s11, s31, s1
	s_add_u32 s0, s30, s6
	s_addc_u32 s1, s31, s7
	s_ashr_i32 s6, s25, 3
	s_abs_i32 s16, s6
	s_mul_hi_u32 s17, s16, s15
	s_mul_i32 s28, s17, s74
	s_sub_i32 s16, s16, s28
	s_ashr_i32 s7, s25, 31
	s_add_i32 s28, s17, 1
	s_sub_i32 s29, s16, s74
	s_cmp_ge_u32 s16, s74
	s_cselect_b32 s17, s28, s17
	s_cselect_b32 s16, s29, s16
	s_add_i32 s28, s17, 1
	s_cmp_ge_u32 s16, s74
	s_cselect_b32 s16, s28, s17
	s_xor_b32 s16, s16, s7
	s_sub_i32 s7, s16, s7
	s_mul_i32 s16, s7, s74
	s_sub_i32 s28, s6, s16
	s_max_i32 s6, s28, 4
	s_add_i32 s6, s6, -4
	s_lshl_b32 s16, s28, 6
	s_add_u32 s10, s10, 0xe240000
	s_addc_u32 s11, s11, 0
	s_min_u32 s29, s6, s75
	s_lshl_b32 s17, s29, 6
	s_lshl_b32 s7, s7, s70
	s_add_i32 s6, s7, s16
	s_add_i32 s33, s7, s17
	s_lshl_b32 s58, s43, 1
	s_add_u32 s16, s10, s58
	s_addc_u32 s17, s11, 0
	v_mov_b32_e32 v163, v1
	v_or_b32_e32 v0, s6, v190
	v_lshl_add_u64 v[168:169], s[16:17], 0, v[162:163]
	v_mad_i64_i32 v[2:3], s[16:17], v0, s18, v[168:169]
	v_or_b32_e32 v0, 32, v0
	global_load_dwordx4 v[82:85], v[2:3], off
	global_load_dwordx4 v[86:89], v[2:3], off offset:32
	global_load_dwordx4 v[90:93], v[2:3], off offset:64
	global_load_dwordx4 v[94:97], v[2:3], off offset:96
	v_mad_i64_i32 v[2:3], s[16:17], v0, s18, v[168:169]
	global_load_dwordx4 v[98:101], v[2:3], off
	global_load_dwordx4 v[102:105], v[2:3], off offset:32
	global_load_dwordx4 v[106:109], v[2:3], off offset:64
	global_load_dwordx4 v[110:113], v[2:3], off offset:96
	v_add_u32_e32 v0, s33, v202
	v_xor_b32_e32 v0, 32, v0
	v_mov_b64_e32 v[2:3], s[10:11]
	v_mad_i64_i32 v[2:3], s[10:11], v0, s18, v[2:3]
	v_lshl_add_u64 v[2:3], v[2:3], 0, s[58:59]
	v_lshl_add_u64 v[2:3], v[2:3], 0, v[162:163]
	global_load_dwordx4 v[158:161], v[2:3], off offset:1024
	global_load_dwordx4 v[154:157], v[2:3], off offset:1056
	global_load_dwordx4 v[150:153], v[2:3], off offset:1088
	global_load_dwordx4 v[146:149], v[2:3], off offset:1120
	v_or_b32_e32 v2, s33, v196
	v_mov_b32_e32 v165, v1
	v_ashrrev_i32_e32 v3, 31, v2
	v_lshl_add_u64 v[4:5], s[0:1], 0, v[164:165]
	s_mov_b64 s[0:1], 0x18340000
	v_lshl_add_u64 v[170:171], v[4:5], 0, s[60:61]
	v_lshlrev_b64 v[6:7], 1, v[2:3]
	v_or_b32_e32 v2, 16, v2
	v_mbcnt_lo_u32_b32 v2, -1, 0
	v_mbcnt_hi_u32_b32 v2, -1, v2
	v_lshrrev_b32_e32 v3, 3, v2
	v_sub_u32_e32 v3, v3, v190
	s_mov_b32 s16, 0x8000
	v_mad_i64_i32 v[172:173], s[40:41], v3, s16, v[170:171]
	v_and_b32_e32 v2, 7, v2
	v_lshlrev_b32_e32 v2, 4, v2
	s_lshl_b32 s16, s33, 1
	v_add_u32_e32 v2, s16, v2
	v_mov_b32_e32 v3, 0
	v_lshl_add_u64 v[172:173], v[172:173], 0, v[2:3]
	v_mov_b64_e32 v[2:3], v[172:173]
	s_mov_b32 s38, 0x40000
	s_mov_b32 s39, 0
	s_add_i32 m0, s27, 0xc00
	s_nop 0
	global_load_lds_dwordx4 v[2:3], off
	s_add_i32 m0, m0, 0x400
	v_lshl_add_u64 v[2:3], v[2:3], 0, s[38:39]
	global_load_lds_dwordx4 v[2:3], off
	s_add_i32 m0, m0, 0x400
	v_lshl_add_u64 v[2:3], v[2:3], 0, s[38:39]
	global_load_lds_dwordx4 v[2:3], off
	s_add_i32 m0, m0, 0x400
	v_lshl_add_u64 v[2:3], v[2:3], 0, s[38:39]
	global_load_lds_dwordx4 v[2:3], off
	s_add_i32 m0, m0, 0x400
	v_lshl_add_u64 v[2:3], v[2:3], 0, s[38:39]
	global_load_lds_dwordx4 v[2:3], off
	s_add_i32 m0, m0, 0x400
	v_lshl_add_u64 v[2:3], v[2:3], 0, s[38:39]
	global_load_lds_dwordx4 v[2:3], off
	s_add_i32 m0, m0, 0x400
	v_lshl_add_u64 v[2:3], v[2:3], 0, s[38:39]
	global_load_lds_dwordx4 v[2:3], off
	s_add_i32 m0, m0, 0x400
	v_lshl_add_u64 v[2:3], v[2:3], 0, s[38:39]
	global_load_lds_dwordx4 v[2:3], off
	v_mov_b32_e32 v14, v1
	v_mov_b32_e32 v15, v1
	v_mov_b32_e32 v0, v1
	v_mov_b32_e32 v2, v1
	v_mov_b32_e32 v3, v1
	v_mov_b32_e32 v4, v1
	v_mov_b32_e32 v5, v1
	v_mov_b32_e32 v6, v1
	v_mov_b32_e32 v7, v1
	v_mov_b32_e32 v8, v1
	v_mov_b32_e32 v9, v1
	v_mov_b32_e32 v10, v1
	v_mov_b32_e32 v11, v1
	v_mov_b32_e32 v12, v1
	v_mov_b32_e32 v13, v1
	v_mov_b64_e32 v[48:49], v[14:15]
	v_mov_b64_e32 v[64:65], v[14:15]
	v_mov_b64_e32 v[32:33], v[14:15]
	v_mov_b64_e32 v[46:47], v[12:13]
	v_mov_b64_e32 v[44:45], v[10:11]
	v_mov_b64_e32 v[42:43], v[8:9]
	v_mov_b64_e32 v[40:41], v[6:7]
	v_mov_b64_e32 v[38:39], v[4:5]
	v_mov_b64_e32 v[36:37], v[2:3]
	v_mov_b64_e32 v[34:35], v[0:1]
	v_mov_b64_e32 v[62:63], v[12:13]
	v_mov_b64_e32 v[60:61], v[10:11]
	v_mov_b64_e32 v[58:59], v[8:9]
	v_mov_b64_e32 v[56:57], v[6:7]
	v_mov_b64_e32 v[54:55], v[4:5]
	v_mov_b64_e32 v[52:53], v[2:3]
	v_mov_b64_e32 v[50:51], v[0:1]
	v_mov_b64_e32 v[30:31], v[12:13]
	v_mov_b64_e32 v[28:29], v[10:11]
	v_mov_b64_e32 v[26:27], v[8:9]
	v_mov_b64_e32 v[24:25], v[6:7]
	v_mov_b64_e32 v[22:23], v[4:5]
	v_mov_b64_e32 v[20:21], v[2:3]
	v_mov_b64_e32 v[18:19], v[0:1]
	v_mov_b64_e32 v[16:17], v[14:15]
	s_sub_i32 s7, s29, s28
	v_add_u32_e32 v165, s33, v196
	v_add_u32_e32 v167, s33, v202
	s_mov_b32 s28, 0
	v_mov_b32_e32 v163, 0
	v_mov_b32_e32 v207, 0xf149f2ca
	v_mov_b32_e32 v208, 0xf149f2ca
	v_mov_b32_e32 v206, 0
	v_mov_b64_e32 v[14:15], v[12:13]
	v_mov_b64_e32 v[12:13], v[10:11]
	v_mov_b64_e32 v[10:11], v[8:9]
	v_mov_b64_e32 v[8:9], v[6:7]
	v_mov_b64_e32 v[6:7], v[4:5]
	v_mov_b64_e32 v[4:5], v[2:3]
	v_mov_b64_e32 v[2:3], v[0:1]
	s_mov_b32 s29, 0
	s_cmpk_eq_i32 s28, 0x1e0
	s_cbranch_scc1 .LBB0_354
	s_branch .LBB0_353
.LBB0_352:
	s_waitcnt vmcnt(0)
	v_mov_b64_e32 v[148:149], v[144:145]
	v_mov_b64_e32 v[152:153], v[140:141]
	v_mov_b64_e32 v[156:157], v[136:137]
	v_mov_b64_e32 v[160:161], v[132:133]
	v_mov_b64_e32 v[146:147], v[142:143]
	v_mov_b64_e32 v[150:151], v[138:139]
	v_mov_b64_e32 v[154:155], v[134:135]
	v_mov_b64_e32 v[158:159], v[130:131]
	s_cmpk_eq_i32 s28, 0x1e0
	s_cbranch_scc1 .LBB0_354
; __device__ __forceinline__ f32x16 mfma32(bf16x8 a, bf16x8 b, f32x16 c) { return __builtin_amdgcn_mfma_f32_32x32x16_bf16(a, b, c, 0, 0, 0); }
; __device__ __forceinline__ f32x16 zero16() { return (f32x16){0.f, 0.f, 0.f, 0.f, 0.f, 0.f, 0.f, 0.f, 0.f, 0.f, 0.f, 0.f, 0.f, 0.f, 0.f, 0.f}; }
; __device__ __forceinline__ void na_load(NaFrags& f, const bf16_t* __restrict__ proj, const bf16_t* __restrict__ projT, int ktok, int h, int c, int hh) {
;     const bf16_t* kp = proj + (size_t)(ktok + c) * NPROJ + 512 + h * 64 + 8 * hh;
; #pragma unroll
;     for (int s = 0; s < 4; ++s) f.k[s] = *(const bf16x8*)(kp + 16 * s);
; #pragma unroll
;     for (int dt = 0; dt < 2; ++dt)
; #pragma unroll
;         for (int s2 = 0; s2 < 2; ++s2) { const bf16_t* vp = projT + (size_t)(h * 64 + dt * 32 + c) * MG + (ktok + 16 * s2 + 4 * hh);
;             f.v[dt][s2][0] = *(const u32x2*)vp; f.v[dt][s2][1] = *(const u32x2*)(vp + 8); }
; }
; __device__ __forceinline__ void na_item(const bf16_t* __restrict__ proj, const bf16_t* __restrict__ projT, bf16_t* aout, const float* __restrict__ relb  , int item, int seqlen, LAS unsigned char* lds, int w, int lane) {
;     ...
;         if (t + 1 < 16) na_load(nxt, proj, projT, ktok0 + 32 * (t + 1), h, c, hh);
;         const int kr = rs + (t >> 1), chalf = t & 1, brow = (kr - r + 7) * 31;
; #pragma unroll
;         for (int qh = 0; qh < 2; ++qh) {
;             f32x16 x = zero16();
; #pragma unroll
;             for (int s = 0; s < 4; ++s) x = mfma32(cur.k[s], qf[qh][s], x);
;             const int qc = 32 * qh + c; float mt = -1e30f;
; #pragma unroll
;             for (int rg = 0; rg < 16; ++rg) { const int kc = 32 * chalf + (rg & 3) + 8 * (rg >> 2) + 4 * hh;
;                 const bool valid = (kc >= cs[qh]) && (kc < cs[qh] + 16);
;                 const float sv = fmaf(x[rg], 0.18033688011112042f, bias[brow + kc - qc + 15]) + (valid ? 0.f : -__builtin_inff());
;                 x[rg] = sv; mt = fmaxf(mt, sv); }
;             mt = xhalf_max(mt);
;             if (__builtin_amdgcn_ballot_w64(mt > mrun[qh] + 8.0f) != 0ull) {
;                 const float mnew = fmaxf(mrun[qh], mt), alpha = __builtin_amdgcn_exp2f(mrun[qh] - mnew);
;                 mrun[qh] = mnew; lrun[qh] *= alpha; O[qh][0] *= alpha; O[qh][1] *= alpha; }
.LBB0_353:
	v_add_u32_e32 v0, s28, v167
	v_mad_i64_i32 v[66:67], s[0:1], v0, s18, v[168:169]
	global_load_dwordx4 v[130:133], v[66:67], off offset:1024
	global_load_dwordx4 v[134:137], v[66:67], off offset:1056
	global_load_dwordx4 v[138:141], v[66:67], off offset:1088
	global_load_dwordx4 v[142:145], v[66:67], off offset:1120
.LBB0_354:
	s_waitcnt vmcnt(4)
	s_and_b32 s11, s28, 32
	s_lshl_b32 s11, s11, 1
	v_add_u32_e32 v176, s11, v191
	ds_read_b128 v[126:129], v176
	ds_read_b128 v[118:121], v176 offset:32
	ds_read_b128 v[122:125], v176 offset:4096
	ds_read_b128 v[114:117], v176 offset:4128
	v_mfma_f32_32x32x16_bf16 v[66:81], v[158:161], v[82:85], 0
	s_lshr_b32 s0, s29, 1
	s_add_i32 s10, s7, s0
	s_mul_i32 s10, s10, 31
	v_and_or_b32 v0, s28, 32, v196
	v_sub_u32_e32 v220, s10, v190
	v_lshlrev_b32_e32 v220, 2, v220
	v_lshlrev_b32_e32 v209, 2, v0
	v_mfma_f32_32x32x16_bf16 v[66:81], v[154:157], v[86:89], v[66:81]
	v_add3_u32 v219, s27, v220, v209
	v_add_u32_e32 v219, 0x4a0, v219
	v_sub_u32_e32 v218, v0, v192
	ds_read2_b32 v[210:211], v219 offset1:1
	ds_read2_b32 v[212:213], v219 offset0:2 offset1:3
	ds_read2_b32 v[214:215], v219 offset0:4 offset1:5
	ds_read2_b32 v[216:217], v219 offset0:6 offset1:7
	v_mfma_f32_32x32x16_bf16 v[66:81], v[150:153], v[90:93], v[66:81]
	ds_read2_b32 v[222:223], v219 offset0:16 offset1:17
	ds_read2_b32 v[224:225], v219 offset0:18 offset1:19
	ds_read2_b32 v[226:227], v219 offset0:20 offset1:21
	ds_read2_b32 v[228:229], v219 offset0:22 offset1:23
	v_mfma_f32_32x32x16_bf16 v[66:81], v[146:149], v[94:97], v[66:81]
	s_waitcnt lgkmcnt(0)
	s_and_b32 s11, s29, 1
	s_cmp_eq_u32 s11, 0
	s_cbranch_scc1 .Lna_skipv
	s_cmp_eq_u32 s29, 15
	s_cbranch_scc1 .Lna_skipv
	s_lshl_b32 s38, s28, 1
	s_add_i32 s38, s38, 64
	s_mov_b32 s39, 0
	v_lshl_add_u64 v[174:175], v[172:173], 0, s[38:39]
	s_mov_b32 s38, 0x40000
	s_mov_b32 s39, 0
	s_add_i32 m0, s27, 0xc00
	s_nop 0
	global_load_lds_dwordx4 v[174:175], off
	s_add_i32 m0, m0, 0x400
	v_lshl_add_u64 v[174:175], v[174:175], 0, s[38:39]
	global_load_lds_dwordx4 v[174:175], off
	s_add_i32 m0, m0, 0x400
	v_lshl_add_u64 v[174:175], v[174:175], 0, s[38:39]
	global_load_lds_dwordx4 v[174:175], off
	s_add_i32 m0, m0, 0x400
	v_lshl_add_u64 v[174:175], v[174:175], 0, s[38:39]
	global_load_lds_dwordx4 v[174:175], off
	s_add_i32 m0, m0, 0x400
	v_lshl_add_u64 v[174:175], v[174:175], 0, s[38:39]
	global_load_lds_dwordx4 v[174:175], off
	s_add_i32 m0, m0, 0x400
	v_lshl_add_u64 v[174:175], v[174:175], 0, s[38:39]
	global_load_lds_dwordx4 v[174:175], off
	s_add_i32 m0, m0, 0x400
	v_lshl_add_u64 v[174:175], v[174:175], 0, s[38:39]
	global_load_lds_dwordx4 v[174:175], off
	s_add_i32 m0, m0, 0x400
	v_lshl_add_u64 v[174:175], v[174:175], 0, s[38:39]
	global_load_lds_dwordx4 v[174:175], off
.Lna_skipv:
	s_nop 11
	v_fmac_f32_e32 v210, 0x3e38aa3b, v66
	v_fmac_f32_e32 v211, 0x3e38aa3b, v67
	v_fmac_f32_e32 v212, 0x3e38aa3b, v68
	v_fmac_f32_e32 v213, 0x3e38aa3b, v69
	v_fmac_f32_e32 v214, 0x3e38aa3b, v70
	v_fmac_f32_e32 v215, 0x3e38aa3b, v71
	v_fmac_f32_e32 v216, 0x3e38aa3b, v72
	v_fmac_f32_e32 v217, 0x3e38aa3b, v73
	v_fmac_f32_e32 v222, 0x3e38aa3b, v74
	v_fmac_f32_e32 v223, 0x3e38aa3b, v75
	v_fmac_f32_e32 v224, 0x3e38aa3b, v76
	v_fmac_f32_e32 v225, 0x3e38aa3b, v77
	v_fmac_f32_e32 v226, 0x3e38aa3b, v78
	v_fmac_f32_e32 v227, 0x3e38aa3b, v79
	v_fmac_f32_e32 v228, 0x3e38aa3b, v80
	v_fmac_f32_e32 v229, 0x3e38aa3b, v81
	v_add_u32_e32 v230, 1, v218
	v_add_u32_e32 v231, 2, v218
	v_add_u32_e32 v233, 3, v218
	v_cmp_gt_u32_e32 vcc, 16, v218
	v_cmp_gt_u32_e64 s[0:1], 16, v230
	v_cmp_gt_u32_e64 s[38:39], 16, v231
	v_cmp_gt_u32_e64 s[40:41], 16, v233
	v_cndmask_b32_e32 v66, v241, v210, vcc
	v_cndmask_b32_e64 v67, v241, v211, s[0:1]
	v_cndmask_b32_e64 v68, v241, v212, s[38:39]
	v_cndmask_b32_e64 v69, v241, v213, s[40:41]
	v_add_u32_e32 v220, 4, v218
	v_add_u32_e32 v230, 5, v218
	v_add_u32_e32 v231, 6, v218
	v_add_u32_e32 v233, 7, v218
	v_cmp_gt_u32_e32 vcc, 16, v220
	v_cmp_gt_u32_e64 s[0:1], 16, v230
	v_cmp_gt_u32_e64 s[38:39], 16, v231
	v_cmp_gt_u32_e64 s[40:41], 16, v233
	v_cndmask_b32_e32 v70, v241, v214, vcc
	v_cndmask_b32_e64 v71, v241, v215, s[0:1]
	v_cndmask_b32_e64 v72, v241, v216, s[38:39]
	v_cndmask_b32_e64 v73, v241, v217, s[40:41]
	v_add_u32_e32 v220, 16, v218
	v_add_u32_e32 v230, 17, v218
	v_add_u32_e32 v231, 18, v218
	v_add_u32_e32 v233, 19, v218
	v_cmp_gt_u32_e32 vcc, 16, v220
	v_cmp_gt_u32_e64 s[0:1], 16, v230
	v_cmp_gt_u32_e64 s[38:39], 16, v231
	v_cmp_gt_u32_e64 s[40:41], 16, v233
	v_cndmask_b32_e32 v74, v241, v222, vcc
	v_cndmask_b32_e64 v75, v241, v223, s[0:1]
	v_cndmask_b32_e64 v76, v241, v224, s[38:39]
	v_cndmask_b32_e64 v77, v241, v225, s[40:41]
	v_add_u32_e32 v220, 20, v218
	v_add_u32_e32 v230, 21, v218
	v_add_u32_e32 v231, 22, v218
	v_add_u32_e32 v233, 23, v218
	v_cmp_gt_u32_e32 vcc, 16, v220
	v_cmp_gt_u32_e64 s[0:1], 16, v230
	v_cmp_gt_u32_e64 s[38:39], 16, v231
	v_cmp_gt_u32_e64 s[40:41], 16, v233
	v_cndmask_b32_e32 v78, v241, v226, vcc
	v_cndmask_b32_e64 v79, v241, v227, s[0:1]
	v_cndmask_b32_e64 v80, v241, v228, s[38:39]
	v_cndmask_b32_e64 v81, v241, v229, s[40:41]
	v_max3_f32 v221, v66, s19, v67
	v_max3_f32 v221, v221, v68, v69
	v_max3_f32 v221, v221, v70, v71
	v_max3_f32 v221, v221, v72, v73
	v_max3_f32 v221, v221, v74, v75
	v_max3_f32 v221, v221, v76, v77
	v_max3_f32 v221, v221, v78, v79
	v_max3_f32 v221, v221, v80, v81
	v_mov_b32_e32 v222, v221
	s_nop 1
	v_permlane32_swap_b32_e32 v221, v222
	v_max_f32_e32 v222, v222, v222
	v_max_f32_e32 v221, v221, v221
	v_max_f32_e32 v221, v221, v222
	v_add_f32_e32 v222, 0x41000000, v208
	v_cmp_gt_f32_e32 vcc, v221, v222
	s_cbranch_vccz .LBB0_356
	v_max_f32_e32 v221, v221, v221
	v_max_f32_e32 v222, v208, v208
	v_max_f32_e32 v221, v222, v221
	v_sub_f32_e32 v208, v208, v221
	v_exp_f32_e32 v208, v208
	s_nop 0
	v_mul_f32_e32 v206, v206, v208
	v_pk_mul_f32 v[64:65], v[64:65], v[208:209] op_sel_hi:[1,0]
	v_pk_mul_f32 v[62:63], v[62:63], v[208:209] op_sel_hi:[1,0]
	v_pk_mul_f32 v[60:61], v[60:61], v[208:209] op_sel_hi:[1,0]
	v_pk_mul_f32 v[58:59], v[58:59], v[208:209] op_sel_hi:[1,0]
	v_pk_mul_f32 v[56:57], v[56:57], v[208:209] op_sel_hi:[1,0]
	v_pk_mul_f32 v[54:55], v[54:55], v[208:209] op_sel_hi:[1,0]
	v_pk_mul_f32 v[52:53], v[52:53], v[208:209] op_sel_hi:[1,0]
	v_pk_mul_f32 v[50:51], v[50:51], v[208:209] op_sel_hi:[1,0]
	v_pk_mul_f32 v[48:49], v[48:49], v[208:209] op_sel_hi:[1,0]
	v_pk_mul_f32 v[46:47], v[46:47], v[208:209] op_sel_hi:[1,0]
	v_pk_mul_f32 v[44:45], v[44:45], v[208:209] op_sel_hi:[1,0]
	v_pk_mul_f32 v[42:43], v[42:43], v[208:209] op_sel_hi:[1,0]
	v_pk_mul_f32 v[40:41], v[40:41], v[208:209] op_sel_hi:[1,0]
	v_pk_mul_f32 v[38:39], v[38:39], v[208:209] op_sel_hi:[1,0]
	v_pk_mul_f32 v[36:37], v[36:37], v[208:209] op_sel_hi:[1,0]
	v_pk_mul_f32 v[34:35], v[34:35], v[208:209] op_sel_hi:[1,0]
	v_mov_b32_e32 v208, v221
